# v63 + out-proj: accumulators start at zero, residual x loaded in the epilogue in 4 chunks with counted vmcnt (one chunk ahead) and added before the store
# speedup vs baseline: 1.0016x; 1.0016x over previous
; DI int tid() { int t = threadIdx.x; asm volatile("" : "+v"(t)); return t; }
; DI void out_tile(const Params& p, int l, int mi, int ni, char* lds) {
;   const int m0 = mi * 256, n0 = ni * 256;
;   f32x16 acc[4][2];
;   const float* xs = (l == 0) ? p.x : p.X;
;   const int t = tid(), lane = t & 63, w = t >> 6, wm = w >> 2, wn = w & 3, r = lane & 31, hf = lane >> 5;
; #pragma unroll
;   for (int mt = 0; mt < 4; ++mt) {
;     const float* xr = xs + (size_t)(m0 + wm * 128 + mt * 32 + r) * DM + n0 + wn * 64 + 4 * hf;
; #pragma unroll
;     for (int nt = 0; nt < 2; ++nt)
; #pragma unroll
;       for (int g = 0; g < 4; ++g) {
;         const f32x4 v = *(const f32x4*)(xr + nt * 32 + 8 * g);
;         acc[mt][nt][4 * g] = v[0]; acc[mt][nt][4 * g + 1] = v[1]; acc[mt][nt][4 * g + 2] = v[2]; acc[mt][nt][4 * g + 3] = v[3];
;       }
;   }
;   gemm_main<true, false, false>(p.MIX + (size_t)m0 * 2048, 2048, p.WoutT + ((size_t)l * 2048 + n0) * 2048, 2048, 2048, lds, acc, nullptr);
.LBB0_290:
	s_and_b32 s0, s63, 31
	s_ashr_i32 s84, s81, 5
	s_lshl_b32 s4, s0, 20
	s_lshl_b32 s0, s84, 8
	v_mov_b32_e32 v0, v222
	s_ashr_i32 s1, s0, 31
	v_ashrrev_i32_e32 v2, 1, v0
	s_and_b32 s85, s81, 31
	v_and_b32_e32 v2, 0xffffff80, v2
	s_lshl_b64 s[82:83], s[0:1], 2
	v_bfe_u32 v173, v0, 6, 2
	v_lshl_add_u32 v2, s85, 8, v2
	s_add_u32 s82, s52, s82
	v_bfe_u32 v171, v0, 5, 1
	v_and_or_b32 v168, v0, 31, v2
	s_addc_u32 s83, s2, s83
	v_lshlrev_b32_e32 v0, 8, v173
	v_lshl_add_u64 v[2:3], s[82:83], 0, v[0:1]
	v_lshlrev_b32_e32 v0, 4, v171
	v_ashrrev_i32_e32 v169, 31, v168
	v_lshl_add_u64 v[2:3], v[2:3], 0, v[0:1]
	v_lshlrev_b64 v[4:5], 13, v[168:169]
	v_or_b32_e32 v166, 32, v168
	v_lshl_add_u64 v[4:5], v[2:3], 0, v[4:5]
	v_ashrrev_i32_e32 v167, 31, v166
	v_lshlrev_b64 v[4:5], 13, v[166:167]
	v_or_b32_e32 v164, 64, v168
	v_lshl_add_u64 v[4:5], v[2:3], 0, v[4:5]
	v_ashrrev_i32_e32 v165, 31, v164
	v_lshlrev_b64 v[4:5], 13, v[164:165]
	v_or_b32_e32 v162, 0x60, v168
	v_lshl_add_u64 v[4:5], v[2:3], 0, v[4:5]
	v_ashrrev_i32_e32 v163, 31, v162
	v_lshlrev_b64 v[4:5], 13, v[162:163]
	v_lshl_add_u64 v[14:15], v[2:3], 0, v[4:5]
	v_mov_b32_e32 v176, v222
	s_nop 0
	s_lshl_b32 s82, s85, 20
	s_add_u32 s86, s34, s82
	v_ashrrev_i32_e32 v174, 3, v176
	v_ashrrev_i32_e32 v175, 31, v174
	s_addc_u32 s87, s35, 0
	s_lshl_b64 s[82:83], s[0:1], 12
	v_lshlrev_b64 v[180:181], 12, v[174:175]
	s_waitcnt vmcnt(2)
	v_lshlrev_b32_e32 v132, 4, v176
	s_add_u32 s88, s53, s82
	v_lshl_add_u64 v[130:131], s[86:87], 0, v[180:181]
	v_and_b32_e32 v182, 0x70, v132
	v_mov_b32_e32 v183, v1
	s_addc_u32 s89, s62, s83
	v_lshl_add_u64 v[130:131], v[130:131], 0, v[182:183]
	v_lshl_add_u64 v[132:133], s[88:89], 0, v[180:181]
	s_waitcnt vmcnt(1)
	v_add_co_u32_e32 v138, vcc, s54, v130
	v_lshl_add_u64 v[134:135], v[132:133], 0, v[182:183]
	s_nop 0
	v_addc_co_u32_e32 v139, vcc, 0, v131, vcc
	s_waitcnt vmcnt(0)
	v_add_co_u32_e32 v142, vcc, s54, v134
	global_load_dwordx4 v[184:187], v[130:131], off
	global_load_dwordx4 v[188:191], v[134:135], off
	v_addc_co_u32_e32 v143, vcc, 0, v135, vcc
	v_add_co_u32_e32 v146, vcc, s55, v130
	global_load_dwordx4 v[192:195], v[138:139], off
	s_nop 0
	v_addc_co_u32_e32 v147, vcc, 0, v131, vcc
	v_add_co_u32_e32 v150, vcc, s55, v134
	global_load_dwordx4 v[196:199], v[142:143], off
	s_nop 0
	v_addc_co_u32_e32 v151, vcc, 0, v135, vcc
	v_add_co_u32_e32 v154, vcc, s8, v130
	global_load_dwordx4 v[200:203], v[146:147], off
	s_nop 0
	v_addc_co_u32_e32 v155, vcc, 0, v131, vcc
	v_add_co_u32_e32 v158, vcc, s8, v134
	global_load_dwordx4 v[204:207], v[150:151], off
	s_nop 0
	v_addc_co_u32_e32 v159, vcc, 0, v135, vcc
	global_load_dwordx4 v[208:211], v[154:155], off
	global_load_dwordx4 v[212:215], v[158:159], off
	s_barrier
; #define G_LOAD(KT) do { const int k0_ = (KT) << 6; _Pragma("unroll") for (int p = 0; p < 4; ++p) { \
;     ra[p] = *(const u32x4*)(ap + (size_t)(64 * p) * lda + k0_); rb[p] = *(const u32x4*)(bp + (size_t)(64 * p) * ldb + k0_); } } while (0)
; template <bool SWAP, bool SSQ, bool ZERO = true>
; DI void gemm_main(const u16* __restrict__ A, int lda, const u16* __restrict__ Bt, int ldb, int K, char* lds,
;                   f32x16 (&acc)[4][2], float* rs_lds) {
;     ...
;   if (ZERO) {
; #pragma unroll
;     for (int mt = 0; mt < 4; ++mt)
; #pragma unroll
;       for (int nt = 0; nt < 2; ++nt)
; #pragma unroll
;         for (int i = 0; i < 16; ++i) acc[mt][nt][i] = 0.f;
;   }
;   const int nk = K >> 6;
;   char* const wbase = lds + lr * GS + lc * 16;
;   const char* abase = lds + (wm * 128 + r) * GS + hf * 16;
;   const char* bbase = lds + G_TILE + (wn * 64 + r) * GS + hf * 16;
;     ...
;   G_LOAD(0);
;   __syncthreads();
;   G_WRITE(0);
;   G_LOAD(1);
;   __syncthreads();
	global_load_dwordx4 v[130:133], v[130:131], off offset:128
	s_nop 0
	global_load_dwordx4 v[134:137], v[134:135], off offset:128
	s_nop 0
	global_load_dwordx4 v[138:141], v[138:139], off offset:128
	s_nop 0
	global_load_dwordx4 v[142:145], v[142:143], off offset:128
	s_nop 0
	global_load_dwordx4 v[146:149], v[146:147], off offset:128
	s_nop 0
	global_load_dwordx4 v[150:153], v[150:151], off offset:128
	s_nop 0
	global_load_dwordx4 v[154:157], v[154:155], off offset:128
	s_nop 0
	global_load_dwordx4 v[158:161], v[158:159], off offset:128
	v_and_b32_e32 v175, 31, v176
	v_lshrrev_b32_e32 v177, 1, v176
	v_and_b32_e32 v183, 0xdf, v176
	v_and_or_b32 v179, v177, s7, v175
	v_and_b32_e32 v178, 16, v177
	v_mad_u64_u32 v[174:175], s[88:89], v174, s9, v[182:183]
	v_mad_u64_u32 v[176:177], s[88:89], v179, s9, v[178:179]
	v_mad_u32_u24 v175, v183, s9, v178
	v_lshl_add_u64 v[178:179], v[180:181], 0, s[82:83]
	v_lshl_add_u64 v[180:181], s[4:5], 0, v[180:181]
	v_or_b32_e32 v178, v178, v182
	v_or_b32_e32 v180, v180, v182
	s_mov_b32 s85, 2
	v_lshlrev_b32_e32 v172, 6, v173
	v_lshlrev_b32_e32 v170, 2, v171
	s_mov_b32 s86, 0
	v_lshl_add_u64 v[178:179], s[76:77], 0, v[178:179]
	v_lshl_add_u64 v[180:181], s[34:35], 0, v[180:181]
	s_mov_b64 s[82:83], 0
	s_waitcnt vmcnt(15)
	ds_write_b128 v174, v[184:187]
	s_waitcnt vmcnt(14)
	ds_write_b128 v174, v[188:191] offset:36864
	s_waitcnt vmcnt(13)
	ds_write_b128 v174, v[192:195] offset:9216
	s_waitcnt vmcnt(12)
	ds_write_b128 v174, v[196:199] offset:46080
	s_waitcnt vmcnt(11)
	ds_write_b128 v174, v[200:203] offset:18432
	s_waitcnt vmcnt(10)
	ds_write_b128 v174, v[204:207] offset:55296
	s_waitcnt vmcnt(9)
	ds_write_b128 v174, v[208:211] offset:27648
	s_waitcnt vmcnt(8)
	ds_write_b128 v174, v[212:215] offset:64512
	s_add_i32 s4, s85, -2
	s_and_b32 s4, s4, 2
	s_mul_i32 s4, s4, 0x9000
	v_add_u32_e32 v177, s4, v176
	v_add_u32_e32 v240, s4, v175
	v_mov_b32_e32 v2, 0
	v_mov_b32_e32 v3, 0
	v_mov_b32_e32 v4, 0
	v_mov_b32_e32 v5, 0
	v_mov_b32_e32 v6, 0
	v_mov_b32_e32 v7, 0
	v_mov_b32_e32 v8, 0
	v_mov_b32_e32 v9, 0
	v_mov_b32_e32 v10, 0
	v_mov_b32_e32 v11, 0
	v_mov_b32_e32 v12, 0
	v_mov_b32_e32 v13, 0
	v_mov_b32_e32 v14, 0
	v_mov_b32_e32 v15, 0
	v_mov_b32_e32 v16, 0
	v_mov_b32_e32 v17, 0
	v_mov_b32_e32 v18, 0
	v_mov_b32_e32 v19, 0
	v_mov_b32_e32 v20, 0
	v_mov_b32_e32 v21, 0
	v_mov_b32_e32 v22, 0
	v_mov_b32_e32 v23, 0
	v_mov_b32_e32 v24, 0
	v_mov_b32_e32 v25, 0
	v_mov_b32_e32 v26, 0
	v_mov_b32_e32 v27, 0
	v_mov_b32_e32 v28, 0
	v_mov_b32_e32 v29, 0
	v_mov_b32_e32 v30, 0
	v_mov_b32_e32 v31, 0
	v_mov_b32_e32 v32, 0
	v_mov_b32_e32 v33, 0
	v_mov_b32_e32 v34, 0
	v_mov_b32_e32 v35, 0
	v_mov_b32_e32 v36, 0
	v_mov_b32_e32 v37, 0
	v_mov_b32_e32 v38, 0
	v_mov_b32_e32 v39, 0
	v_mov_b32_e32 v40, 0
	v_mov_b32_e32 v41, 0
	v_mov_b32_e32 v42, 0
	v_mov_b32_e32 v43, 0
	v_mov_b32_e32 v44, 0
	v_mov_b32_e32 v45, 0
	v_mov_b32_e32 v46, 0
	v_mov_b32_e32 v47, 0
	v_mov_b32_e32 v48, 0
	v_mov_b32_e32 v49, 0
	v_mov_b32_e32 v50, 0
	v_mov_b32_e32 v51, 0
	v_mov_b32_e32 v52, 0
	v_mov_b32_e32 v53, 0
	v_mov_b32_e32 v54, 0
	v_mov_b32_e32 v55, 0
	v_mov_b32_e32 v56, 0
	v_mov_b32_e32 v57, 0
	v_mov_b32_e32 v58, 0
	v_mov_b32_e32 v59, 0
	v_mov_b32_e32 v60, 0
	v_mov_b32_e32 v61, 0
	v_mov_b32_e32 v62, 0
	v_mov_b32_e32 v63, 0
	v_mov_b32_e32 v64, 0
	v_mov_b32_e32 v65, 0
	v_mov_b32_e32 v66, 0
	v_mov_b32_e32 v67, 0
	v_mov_b32_e32 v68, 0
	v_mov_b32_e32 v69, 0
	v_mov_b32_e32 v70, 0
	v_mov_b32_e32 v71, 0
	v_mov_b32_e32 v72, 0
	v_mov_b32_e32 v73, 0
	v_mov_b32_e32 v74, 0
	v_mov_b32_e32 v75, 0
	v_mov_b32_e32 v76, 0
	v_mov_b32_e32 v77, 0
	v_mov_b32_e32 v78, 0
	v_mov_b32_e32 v79, 0
	v_mov_b32_e32 v80, 0
	v_mov_b32_e32 v81, 0
	v_mov_b32_e32 v82, 0
	v_mov_b32_e32 v83, 0
	v_mov_b32_e32 v84, 0
	v_mov_b32_e32 v85, 0
	v_mov_b32_e32 v86, 0
	v_mov_b32_e32 v87, 0
	v_mov_b32_e32 v88, 0
	v_mov_b32_e32 v89, 0
	v_mov_b32_e32 v90, 0
	v_mov_b32_e32 v91, 0
	v_mov_b32_e32 v92, 0
	v_mov_b32_e32 v93, 0
	v_mov_b32_e32 v94, 0
	v_mov_b32_e32 v95, 0
	v_mov_b32_e32 v96, 0
	v_mov_b32_e32 v97, 0
	v_mov_b32_e32 v98, 0
	v_mov_b32_e32 v99, 0
	v_mov_b32_e32 v100, 0
	v_mov_b32_e32 v101, 0
	v_mov_b32_e32 v102, 0
	v_mov_b32_e32 v103, 0
	v_mov_b32_e32 v104, 0
	v_mov_b32_e32 v105, 0
	v_mov_b32_e32 v106, 0
	v_mov_b32_e32 v107, 0
	v_mov_b32_e32 v108, 0
	v_mov_b32_e32 v109, 0
	v_mov_b32_e32 v110, 0
	v_mov_b32_e32 v111, 0
	v_mov_b32_e32 v112, 0
	v_mov_b32_e32 v113, 0
	v_mov_b32_e32 v114, 0
	v_mov_b32_e32 v115, 0
	v_mov_b32_e32 v116, 0
	v_mov_b32_e32 v117, 0
	v_mov_b32_e32 v118, 0
	v_mov_b32_e32 v119, 0
	v_mov_b32_e32 v120, 0
	v_mov_b32_e32 v121, 0
	v_mov_b32_e32 v122, 0
	v_mov_b32_e32 v123, 0
	v_mov_b32_e32 v124, 0
	v_mov_b32_e32 v125, 0
	v_mov_b32_e32 v126, 0
	v_mov_b32_e32 v127, 0
	v_mov_b32_e32 v128, 0
	v_mov_b32_e32 v129, 0
	s_waitcnt lgkmcnt(0)
	s_barrier
	s_branch .LBB0_292

; DI void out_tile(const Params& p, int l, int mi, int ni, char* lds) {
;     ...
;     const float* xr = xs + (size_t)(m0 + wm * 128 + mt * 32 + r) * DM + n0 + wn * 64 + 4 * hf;
; #pragma unroll
;     for (int nt = 0; nt < 2; ++nt)
; #pragma unroll
;       for (int g = 0; g < 4; ++g) {
;         const f32x4 v = *(const f32x4*)(xr + nt * 32 + 8 * g);
;         acc[mt][nt][4 * g] = v[0]; acc[mt][nt][4 * g + 1] = v[1]; acc[mt][nt][4 * g + 2] = v[2]; acc[mt][nt][4 * g + 3] = v[3];
;       }
;   }
;   gemm_main<true, false, false>(p.MIX + (size_t)m0 * 2048, 2048, p.WoutT + ((size_t)l * 2048 + n0) * 2048, 2048, 2048, lds, acc, nullptr);
; #pragma unroll
;   for (int mt = 0; mt < 4; ++mt) {
;     const size_t rowoff = (size_t)(m0 + wm * 128 + mt * 32 + r) * DM + n0 + wn * 64 + 4 * hf;
;     const size_t rowoffb = (size_t)(m0 + wm * 128 + mt * 32 + r) * DM + n0 + wn * 64 + 8 * hf;
;     float pss = 0.f;
; #pragma unroll
;     for (int nt = 0; nt < 2; ++nt)
; #pragma unroll
;       for (int a = 0; a < 2; ++a) {
;         float xq[2][4];
; #pragma unroll
;         for (int gg = 0; gg < 2; ++gg) {
;           const int g = 2 * a + gg;
;           f32x4 xo = {acc[mt][nt][4 * g], acc[mt][nt][4 * g + 1], acc[mt][nt][4 * g + 2], acc[mt][nt][4 * g + 3]};
;           *(f32x4*)(p.X + rowoff + nt * 32 + 8 * g) = xo;
;           xq[gg][0] = xo[0]; xq[gg][1] = xo[1]; xq[gg][2] = xo[2]; xq[gg][3] = xo[3];
;           pss = fmaf(xo[0], xo[0], pss); pss = fmaf(xo[1], xo[1], pss); pss = fmaf(xo[2], xo[2], pss); pss = fmaf(xo[3], xo[3], pss);
;         }
;         st8_pair_bf16(p.XB + rowoffb + nt * 32 + 16 * a, xq[0], xq[1]);
;       }
;     pss = xhalf_sum(pss);
;     if (hf == 0) p.XSS[(size_t)(m0 + wm * 128 + mt * 32 + r) * 32 + ni * 4 + wn] = pss;
;   }
.LBB0_296:
	s_waitcnt vmcnt(7)
	v_mov_b32_e32 v131, s1
	v_or_b32_e32 v130, s0, v172
	v_lshlrev_b64 v[132:133], 11, v[168:169]
	s_waitcnt vmcnt(6)
	v_lshl_add_u64 v[136:137], v[132:133], 0, v[130:131]
	v_lshl_add_u64 v[134:135], v[136:137], 2, s[38:39]
	v_lshlrev_b32_e32 v132, 2, v170
	v_mov_b32_e32 v133, v1
	s_waitcnt vmcnt(5)
	v_lshl_add_u64 v[138:139], v[134:135], 0, v[132:133]
	s_sub_u32 s88, s52, s38
	s_subb_u32 s89, s2, s39
	v_lshl_add_u64 v[246:247], v[138:139], 0, s[88:89]
	global_load_dwordx4 v[176:179], v[246:247], off
	global_load_dwordx4 v[180:183], v[246:247], off offset:32
	global_load_dwordx4 v[184:187], v[246:247], off offset:64
	global_load_dwordx4 v[188:191], v[246:247], off offset:96
	global_load_dwordx4 v[192:195], v[246:247], off offset:128
	global_load_dwordx4 v[196:199], v[246:247], off offset:160
	global_load_dwordx4 v[200:203], v[246:247], off offset:192
	global_load_dwordx4 v[204:207], v[246:247], off offset:224
	v_add_co_u32_e32 v242, vcc, 0x40000, v246
	s_nop 1
	v_addc_co_u32_e32 v243, vcc, 0, v247, vcc
	global_load_dwordx4 v[208:211], v[242:243], off
	global_load_dwordx4 v[212:215], v[242:243], off offset:32
	global_load_dwordx4 v[216:219], v[242:243], off offset:64
	global_load_dwordx4 v[140:143], v[242:243], off offset:96
	global_load_dwordx4 v[144:147], v[242:243], off offset:128
	global_load_dwordx4 v[148:151], v[242:243], off offset:160
	global_load_dwordx4 v[152:155], v[242:243], off offset:192
	global_load_dwordx4 v[156:159], v[242:243], off offset:224
	s_waitcnt vmcnt(8)
	v_add_f32_e32 v114, v114, v176
	v_add_f32_e32 v115, v115, v177
	v_add_f32_e32 v116, v116, v178
	v_add_f32_e32 v117, v117, v179
	v_add_f32_e32 v118, v118, v180
	v_add_f32_e32 v119, v119, v181
	v_add_f32_e32 v120, v120, v182
	v_add_f32_e32 v121, v121, v183
	v_add_f32_e32 v122, v122, v184
	v_add_f32_e32 v123, v123, v185
	v_add_f32_e32 v124, v124, v186
	v_add_f32_e32 v125, v125, v187
	v_add_f32_e32 v126, v126, v188
	v_add_f32_e32 v127, v127, v189
	v_add_f32_e32 v128, v128, v190
	v_add_f32_e32 v129, v129, v191
	v_add_f32_e32 v98, v98, v192
	v_add_f32_e32 v99, v99, v193
	v_add_f32_e32 v100, v100, v194
	v_add_f32_e32 v101, v101, v195
	v_add_f32_e32 v102, v102, v196
	v_add_f32_e32 v103, v103, v197
	v_add_f32_e32 v104, v104, v198
	v_add_f32_e32 v105, v105, v199
	v_add_f32_e32 v106, v106, v200
	v_add_f32_e32 v107, v107, v201
	v_add_f32_e32 v108, v108, v202
	v_add_f32_e32 v109, v109, v203
	v_add_f32_e32 v110, v110, v204
	v_add_f32_e32 v111, v111, v205
	v_add_f32_e32 v112, v112, v206
	v_add_f32_e32 v113, v113, v207
	v_add_co_u32_e32 v242, vcc, 0x40000, v242
	s_nop 1
	v_addc_co_u32_e32 v243, vcc, 0, v243, vcc
	global_load_dwordx4 v[176:179], v[242:243], off
	global_load_dwordx4 v[180:183], v[242:243], off offset:32
	global_load_dwordx4 v[184:187], v[242:243], off offset:64
	global_load_dwordx4 v[188:191], v[242:243], off offset:96
	global_load_dwordx4 v[192:195], v[242:243], off offset:128
	global_load_dwordx4 v[196:199], v[242:243], off offset:160
	global_load_dwordx4 v[200:203], v[242:243], off offset:192
	global_load_dwordx4 v[204:207], v[242:243], off offset:224
	v_add_co_u32_e32 v244, vcc, 0x40000, v242
	s_nop 1
	v_addc_co_u32_e32 v245, vcc, 0, v243, vcc
	v_fma_f32 v134, v114, v114, 0
	v_fmac_f32_e32 v134, v115, v115
	v_fmac_f32_e32 v134, v116, v116
	v_fmac_f32_e32 v134, v117, v117
	v_fmac_f32_e32 v134, v118, v118
	v_fmac_f32_e32 v134, v119, v119
	v_fmac_f32_e32 v134, v120, v120
	v_fmac_f32_e32 v134, v121, v121
	v_fmac_f32_e32 v134, v122, v122
	v_fmac_f32_e32 v134, v123, v123
	v_fmac_f32_e32 v134, v124, v124
	v_fmac_f32_e32 v134, v125, v125
	v_fmac_f32_e32 v134, v126, v126
	v_fmac_f32_e32 v134, v127, v127
	v_fmac_f32_e32 v134, v128, v128
	v_fmac_f32_e32 v134, v129, v129
	v_fmac_f32_e32 v134, v98, v98
	v_fmac_f32_e32 v134, v99, v99
	v_fmac_f32_e32 v134, v100, v100
	v_fmac_f32_e32 v134, v101, v101
	v_fmac_f32_e32 v134, v102, v102
	v_fmac_f32_e32 v134, v103, v103
	v_fmac_f32_e32 v134, v104, v104
	v_fmac_f32_e32 v134, v105, v105
	v_fmac_f32_e32 v134, v106, v106
	global_store_dwordx4 v[138:139], v[114:117], off
	v_lshl_add_u64 v[136:137], v[136:137], 1, s[40:41]
	v_fmac_f32_e32 v134, v107, v107
	v_cvt_pk_bf16_f32 v114, v114, v115
	v_cvt_pk_bf16_f32 v115, v116, v117
	v_cvt_pk_bf16_f32 v116, v118, v119
	v_cvt_pk_bf16_f32 v117, v120, v121
	v_lshl_add_u64 v[136:137], v[136:137], 0, v[0:1]
	v_permlane32_swap_b32_e32 v114, v116
	v_permlane32_swap_b32_e32 v115, v117
	v_fmac_f32_e32 v134, v108, v108
	global_store_dwordx4 v[138:139], v[118:121], off offset:32
	global_store_dwordx4 v[136:137], v[114:117], off
	global_store_dwordx4 v[138:139], v[122:125], off offset:64
	v_fmac_f32_e32 v134, v109, v109
	v_cvt_pk_bf16_f32 v114, v122, v123
	v_cvt_pk_bf16_f32 v115, v124, v125
	v_cvt_pk_bf16_f32 v116, v126, v127
	v_cvt_pk_bf16_f32 v117, v128, v129
	s_nop 0
	v_permlane32_swap_b32_e32 v114, v116
	v_permlane32_swap_b32_e32 v115, v117
	v_fmac_f32_e32 v134, v110, v110
	global_store_dwordx4 v[138:139], v[126:129], off offset:96
	global_store_dwordx4 v[136:137], v[114:117], off offset:32
	global_store_dwordx4 v[138:139], v[98:101], off offset:128
	v_fmac_f32_e32 v134, v111, v111
	v_fmac_f32_e32 v134, v112, v112
	v_cvt_pk_bf16_f32 v98, v98, v99
	v_cvt_pk_bf16_f32 v99, v100, v101
	v_cvt_pk_bf16_f32 v100, v102, v103
	v_cvt_pk_bf16_f32 v101, v104, v105
	s_nop 0
	v_permlane32_swap_b32_e32 v98, v100
	v_permlane32_swap_b32_e32 v99, v101
	global_store_dwordx4 v[138:139], v[102:105], off offset:160
	global_store_dwordx4 v[136:137], v[98:101], off offset:64
	global_store_dwordx4 v[138:139], v[106:109], off offset:192
	v_fmac_f32_e32 v134, v113, v113
	v_cvt_pk_bf16_f32 v98, v106, v107
	v_cvt_pk_bf16_f32 v99, v108, v109
	v_cvt_pk_bf16_f32 v100, v110, v111
	v_cvt_pk_bf16_f32 v101, v112, v113
	s_lshl_b32 s0, s84, 2
	v_permlane32_swap_b32_e32 v98, v100
	v_permlane32_swap_b32_e32 v99, v101
	v_mov_b32_e32 v0, v134
	v_cmp_eq_u32_e32 vcc, 0, v171
	s_ashr_i32 s1, s0, 31
	global_store_dwordx4 v[138:139], v[110:113], off offset:224
	global_store_dwordx4 v[136:137], v[98:101], off offset:96
	v_permlane32_swap_b32_e32 v134, v0
	s_nop 0
	v_lshlrev_b32_e32 v98, 2, v173
	s_and_saveexec_b64 s[82:83], vcc
	s_cbranch_execz .LBB0_298
	v_lshlrev_b64 v[100:101], 7, v[168:169]
	v_lshl_add_u64 v[100:101], s[28:29], 0, v[100:101]
	v_lshl_add_u64 v[100:101], s[0:1], 2, v[100:101]
	v_mov_b32_e32 v99, v1
	v_lshl_add_u64 v[100:101], v[100:101], 0, v[98:99]
	v_add_f32_e32 v0, v134, v0
	global_store_dword v[100:101], v0, off
; DI void out_tile(const Params& p, int l, int mi, int ni, char* lds) {
;     ...
;         const f32x4 v = *(const f32x4*)(xr + nt * 32 + 8 * g);
;         acc[mt][nt][4 * g] = v[0]; acc[mt][nt][4 * g + 1] = v[1]; acc[mt][nt][4 * g + 2] = v[2]; acc[mt][nt][4 * g + 3] = v[3];
;       }
;   }
;   gemm_main<true, false, false>(p.MIX + (size_t)m0 * 2048, 2048, p.WoutT + ((size_t)l * 2048 + n0) * 2048, 2048, 2048, lds, acc, nullptr);
; #pragma unroll
;   for (int mt = 0; mt < 4; ++mt) {
;     const size_t rowoff = (size_t)(m0 + wm * 128 + mt * 32 + r) * DM + n0 + wn * 64 + 4 * hf;
;     const size_t rowoffb = (size_t)(m0 + wm * 128 + mt * 32 + r) * DM + n0 + wn * 64 + 8 * hf;
;     float pss = 0.f;
; #pragma unroll
;     for (int nt = 0; nt < 2; ++nt)
; #pragma unroll
;       for (int a = 0; a < 2; ++a) {
;         float xq[2][4];
; #pragma unroll
;         for (int gg = 0; gg < 2; ++gg) {
;           const int g = 2 * a + gg;
;           f32x4 xo = {acc[mt][nt][4 * g], acc[mt][nt][4 * g + 1], acc[mt][nt][4 * g + 2], acc[mt][nt][4 * g + 3]};
;           *(f32x4*)(p.X + rowoff + nt * 32 + 8 * g) = xo;
;           xq[gg][0] = xo[0]; xq[gg][1] = xo[1]; xq[gg][2] = xo[2]; xq[gg][3] = xo[3];
;           pss = fmaf(xo[0], xo[0], pss); pss = fmaf(xo[1], xo[1], pss); pss = fmaf(xo[2], xo[2], pss); pss = fmaf(xo[3], xo[3], pss);
;         }
;         st8_pair_bf16(p.XB + rowoffb + nt * 32 + 16 * a, xq[0], xq[1]);
;       }
;     pss = xhalf_sum(pss);
;     if (hf == 0) p.XSS[(size_t)(m0 + wm * 128 + mt * 32 + r) * 32 + ni * 4 + wn] = pss;
;   }
.LBB0_298:
	s_or_b64 exec, exec, s[82:83]
	s_waitcnt vmcnt(20)
	v_add_f32_e32 v82, v82, v208
	v_add_f32_e32 v83, v83, v209
	v_add_f32_e32 v84, v84, v210
	v_add_f32_e32 v85, v85, v211
	v_add_f32_e32 v86, v86, v212
	v_add_f32_e32 v87, v87, v213
	v_add_f32_e32 v88, v88, v214
	v_add_f32_e32 v89, v89, v215
	v_add_f32_e32 v90, v90, v216
	v_add_f32_e32 v91, v91, v217
	v_add_f32_e32 v92, v92, v218
	v_add_f32_e32 v93, v93, v219
	v_add_f32_e32 v94, v94, v140
	v_add_f32_e32 v95, v95, v141
	v_add_f32_e32 v96, v96, v142
	v_add_f32_e32 v97, v97, v143
	v_add_f32_e32 v66, v66, v144
	v_add_f32_e32 v67, v67, v145
	v_add_f32_e32 v68, v68, v146
	v_add_f32_e32 v69, v69, v147
	v_add_f32_e32 v70, v70, v148
	v_add_f32_e32 v71, v71, v149
	v_add_f32_e32 v72, v72, v150
	v_add_f32_e32 v73, v73, v151
	v_add_f32_e32 v74, v74, v152
	v_add_f32_e32 v75, v75, v153
	v_add_f32_e32 v76, v76, v154
	v_add_f32_e32 v77, v77, v155
	v_add_f32_e32 v78, v78, v156
	v_add_f32_e32 v79, v79, v157
	v_add_f32_e32 v80, v80, v158
	v_add_f32_e32 v81, v81, v159
	global_load_dwordx4 v[208:211], v[244:245], off
	global_load_dwordx4 v[212:215], v[244:245], off offset:32
	global_load_dwordx4 v[216:219], v[244:245], off offset:64
	global_load_dwordx4 v[140:143], v[244:245], off offset:96
	global_load_dwordx4 v[144:147], v[244:245], off offset:128
	global_load_dwordx4 v[148:151], v[244:245], off offset:160
	global_load_dwordx4 v[152:155], v[244:245], off offset:192
	global_load_dwordx4 v[156:159], v[244:245], off offset:224
	v_lshlrev_b64 v[100:101], 11, v[166:167]
	v_lshl_add_u64 v[102:103], v[100:101], 0, v[130:131]
	v_lshl_add_u64 v[100:101], v[102:103], 2, s[38:39]
	v_lshl_add_u64 v[104:105], v[100:101], 0, v[132:133]
	v_fma_f32 v100, v82, v82, 0
	v_fmac_f32_e32 v100, v83, v83
	v_fmac_f32_e32 v100, v84, v84
	v_fmac_f32_e32 v100, v85, v85
	v_fmac_f32_e32 v100, v86, v86
	v_fmac_f32_e32 v100, v87, v87
	v_fmac_f32_e32 v100, v88, v88
	v_fmac_f32_e32 v100, v89, v89
	v_fmac_f32_e32 v100, v90, v90
	v_fmac_f32_e32 v100, v91, v91
	v_fmac_f32_e32 v100, v92, v92
	v_fmac_f32_e32 v100, v93, v93
	v_fmac_f32_e32 v100, v94, v94
	v_fmac_f32_e32 v100, v95, v95
	v_fmac_f32_e32 v100, v96, v96
	v_fmac_f32_e32 v100, v97, v97
	v_fmac_f32_e32 v100, v66, v66
	v_fmac_f32_e32 v100, v67, v67
	v_fmac_f32_e32 v100, v68, v68
	v_fmac_f32_e32 v100, v69, v69
	v_fmac_f32_e32 v100, v70, v70
	v_fmac_f32_e32 v100, v71, v71
	v_fmac_f32_e32 v100, v72, v72
	v_lshlrev_b32_e32 v0, 3, v171
	v_fmac_f32_e32 v100, v73, v73
	global_store_dwordx4 v[104:105], v[82:85], off
	v_lshl_add_u64 v[102:103], v[102:103], 1, s[40:41]
	v_lshlrev_b32_e32 v0, 1, v0
	v_cvt_pk_bf16_f32 v82, v82, v83
	v_cvt_pk_bf16_f32 v83, v84, v85
	v_cvt_pk_bf16_f32 v84, v86, v87
	v_cvt_pk_bf16_f32 v85, v88, v89
	v_fmac_f32_e32 v100, v74, v74
	v_lshl_add_u64 v[102:103], v[102:103], 0, v[0:1]
	v_permlane32_swap_b32_e32 v82, v84
	v_permlane32_swap_b32_e32 v83, v85
	v_fmac_f32_e32 v100, v75, v75
	global_store_dwordx4 v[104:105], v[86:89], off offset:32
	global_store_dwordx4 v[102:103], v[82:85], off
	global_store_dwordx4 v[104:105], v[90:93], off offset:64
	v_fmac_f32_e32 v100, v76, v76
	v_cvt_pk_bf16_f32 v82, v90, v91
	v_cvt_pk_bf16_f32 v83, v92, v93
	v_cvt_pk_bf16_f32 v84, v94, v95
	v_cvt_pk_bf16_f32 v85, v96, v97
	s_nop 0
	v_permlane32_swap_b32_e32 v82, v84
	v_permlane32_swap_b32_e32 v83, v85
	v_fmac_f32_e32 v100, v77, v77
	global_store_dwordx4 v[104:105], v[94:97], off offset:96
	global_store_dwordx4 v[102:103], v[82:85], off offset:32
	global_store_dwordx4 v[104:105], v[66:69], off offset:128
	v_fmac_f32_e32 v100, v78, v78
	v_fmac_f32_e32 v100, v79, v79
	v_cvt_pk_bf16_f32 v66, v66, v67
	v_cvt_pk_bf16_f32 v67, v68, v69
	v_cvt_pk_bf16_f32 v68, v70, v71
	v_cvt_pk_bf16_f32 v69, v72, v73
	s_nop 0
	v_permlane32_swap_b32_e32 v66, v68
	v_permlane32_swap_b32_e32 v67, v69
	global_store_dwordx4 v[104:105], v[70:73], off offset:160
	global_store_dwordx4 v[102:103], v[66:69], off offset:64
	global_store_dwordx4 v[104:105], v[74:77], off offset:192
	v_fmac_f32_e32 v100, v80, v80
	v_cvt_pk_bf16_f32 v66, v74, v75
	v_cvt_pk_bf16_f32 v67, v76, v77
	v_cvt_pk_bf16_f32 v68, v78, v79
	v_cvt_pk_bf16_f32 v69, v80, v81
	v_fmac_f32_e32 v100, v81, v81
	v_permlane32_swap_b32_e32 v66, v68
	v_permlane32_swap_b32_e32 v67, v69
	global_store_dwordx4 v[104:105], v[78:81], off offset:224
	global_store_dwordx4 v[102:103], v[66:69], off offset:96
	s_nop 1
	v_mov_b32_e32 v66, v100
	s_nop 1
	v_permlane32_swap_b32_e32 v100, v66
	s_and_saveexec_b64 s[82:83], vcc
	s_cbranch_execz .LBB0_300
	v_lshlrev_b64 v[68:69], 7, v[166:167]
	v_lshl_add_u64 v[68:69], s[28:29], 0, v[68:69]
	v_lshl_add_u64 v[68:69], s[0:1], 2, v[68:69]
	v_mov_b32_e32 v99, v1
	v_lshl_add_u64 v[68:69], v[68:69], 0, v[98:99]
	v_add_f32_e32 v66, v100, v66
	global_store_dword v[68:69], v66, off
; DI void out_tile(const Params& p, int l, int mi, int ni, char* lds) {
;     ...
;         const f32x4 v = *(const f32x4*)(xr + nt * 32 + 8 * g);
;         acc[mt][nt][4 * g] = v[0]; acc[mt][nt][4 * g + 1] = v[1]; acc[mt][nt][4 * g + 2] = v[2]; acc[mt][nt][4 * g + 3] = v[3];
;       }
;   }
;   gemm_main<true, false, false>(p.MIX + (size_t)m0 * 2048, 2048, p.WoutT + ((size_t)l * 2048 + n0) * 2048, 2048, 2048, lds, acc, nullptr);
; #pragma unroll
;   for (int mt = 0; mt < 4; ++mt) {
;     const size_t rowoff = (size_t)(m0 + wm * 128 + mt * 32 + r) * DM + n0 + wn * 64 + 4 * hf;
;     const size_t rowoffb = (size_t)(m0 + wm * 128 + mt * 32 + r) * DM + n0 + wn * 64 + 8 * hf;
;     float pss = 0.f;
; #pragma unroll
;     for (int nt = 0; nt < 2; ++nt)
; #pragma unroll
;       for (int a = 0; a < 2; ++a) {
;         float xq[2][4];
; #pragma unroll
;         for (int gg = 0; gg < 2; ++gg) {
;           const int g = 2 * a + gg;
;           f32x4 xo = {acc[mt][nt][4 * g], acc[mt][nt][4 * g + 1], acc[mt][nt][4 * g + 2], acc[mt][nt][4 * g + 3]};
;           *(f32x4*)(p.X + rowoff + nt * 32 + 8 * g) = xo;
;           xq[gg][0] = xo[0]; xq[gg][1] = xo[1]; xq[gg][2] = xo[2]; xq[gg][3] = xo[3];
;           pss = fmaf(xo[0], xo[0], pss); pss = fmaf(xo[1], xo[1], pss); pss = fmaf(xo[2], xo[2], pss); pss = fmaf(xo[3], xo[3], pss);
;         }
;         st8_pair_bf16(p.XB + rowoffb + nt * 32 + 16 * a, xq[0], xq[1]);
;       }
;     pss = xhalf_sum(pss);
;     if (hf == 0) p.XSS[(size_t)(m0 + wm * 128 + mt * 32 + r) * 32 + ni * 4 + wn] = pss;
;   }
.LBB0_300:
	s_or_b64 exec, exec, s[82:83]
	s_waitcnt vmcnt(32)
	v_add_f32_e32 v50, v50, v176
	v_add_f32_e32 v51, v51, v177
	v_add_f32_e32 v52, v52, v178
	v_add_f32_e32 v53, v53, v179
	v_add_f32_e32 v54, v54, v180
	v_add_f32_e32 v55, v55, v181
	v_add_f32_e32 v56, v56, v182
	v_add_f32_e32 v57, v57, v183
	v_add_f32_e32 v58, v58, v184
	v_add_f32_e32 v59, v59, v185
	v_add_f32_e32 v60, v60, v186
	v_add_f32_e32 v61, v61, v187
	v_add_f32_e32 v62, v62, v188
	v_add_f32_e32 v63, v63, v189
	v_add_f32_e32 v64, v64, v190
	v_add_f32_e32 v65, v65, v191
	v_add_f32_e32 v34, v34, v192
	v_add_f32_e32 v35, v35, v193
	v_add_f32_e32 v36, v36, v194
	v_add_f32_e32 v37, v37, v195
	v_add_f32_e32 v38, v38, v196
	v_add_f32_e32 v39, v39, v197
	v_add_f32_e32 v40, v40, v198
	v_add_f32_e32 v41, v41, v199
	v_add_f32_e32 v42, v42, v200
	v_add_f32_e32 v43, v43, v201
	v_add_f32_e32 v44, v44, v202
	v_add_f32_e32 v45, v45, v203
	v_add_f32_e32 v46, v46, v204
	v_add_f32_e32 v47, v47, v205
	v_add_f32_e32 v48, v48, v206
	v_add_f32_e32 v49, v49, v207
	v_lshlrev_b64 v[66:67], 11, v[164:165]
	v_lshl_add_u64 v[68:69], v[66:67], 0, v[130:131]
	v_lshl_add_u64 v[66:67], v[68:69], 2, s[38:39]
	v_mov_b32_e32 v133, v1
	v_lshl_add_u64 v[70:71], v[66:67], 0, v[132:133]
	v_fma_f32 v66, v50, v50, 0
	v_fmac_f32_e32 v66, v51, v51
	v_fmac_f32_e32 v66, v52, v52
	v_fmac_f32_e32 v66, v53, v53
	v_fmac_f32_e32 v66, v54, v54
	v_fmac_f32_e32 v66, v55, v55
	v_fmac_f32_e32 v66, v56, v56
	v_fmac_f32_e32 v66, v57, v57
	v_fmac_f32_e32 v66, v58, v58
	v_fmac_f32_e32 v66, v59, v59
	v_fmac_f32_e32 v66, v60, v60
	v_fmac_f32_e32 v66, v61, v61
	v_fmac_f32_e32 v66, v62, v62
	v_fmac_f32_e32 v66, v63, v63
	v_fmac_f32_e32 v66, v64, v64
	v_fmac_f32_e32 v66, v65, v65
	v_fmac_f32_e32 v66, v34, v34
	v_fmac_f32_e32 v66, v35, v35
	v_fmac_f32_e32 v66, v36, v36
	v_fmac_f32_e32 v66, v37, v37
	v_fmac_f32_e32 v66, v38, v38
	v_fmac_f32_e32 v66, v39, v39
	v_fmac_f32_e32 v66, v40, v40
	v_fmac_f32_e32 v66, v41, v41
	global_store_dwordx4 v[70:71], v[50:53], off
	v_lshl_add_u64 v[68:69], v[68:69], 1, s[40:41]
	v_fmac_f32_e32 v66, v42, v42
	v_cvt_pk_bf16_f32 v50, v50, v51
	v_cvt_pk_bf16_f32 v51, v52, v53
	v_cvt_pk_bf16_f32 v52, v54, v55
	v_cvt_pk_bf16_f32 v53, v56, v57
	v_lshl_add_u64 v[68:69], v[68:69], 0, v[0:1]
	v_permlane32_swap_b32_e32 v50, v52
	v_permlane32_swap_b32_e32 v51, v53
	v_fmac_f32_e32 v66, v43, v43
	global_store_dwordx4 v[70:71], v[54:57], off offset:32
	global_store_dwordx4 v[68:69], v[50:53], off
	global_store_dwordx4 v[70:71], v[58:61], off offset:64
	v_fmac_f32_e32 v66, v44, v44
	v_cvt_pk_bf16_f32 v50, v58, v59
	v_cvt_pk_bf16_f32 v51, v60, v61
	v_cvt_pk_bf16_f32 v52, v62, v63
	v_cvt_pk_bf16_f32 v53, v64, v65
	s_nop 0
	v_permlane32_swap_b32_e32 v50, v52
	v_permlane32_swap_b32_e32 v51, v53
	v_fmac_f32_e32 v66, v45, v45
	global_store_dwordx4 v[70:71], v[62:65], off offset:96
	global_store_dwordx4 v[68:69], v[50:53], off offset:32
	global_store_dwordx4 v[70:71], v[34:37], off offset:128
	v_fmac_f32_e32 v66, v46, v46
	v_fmac_f32_e32 v66, v47, v47
	v_cvt_pk_bf16_f32 v34, v34, v35
	v_cvt_pk_bf16_f32 v35, v36, v37
	v_cvt_pk_bf16_f32 v36, v38, v39
	v_cvt_pk_bf16_f32 v37, v40, v41
	s_nop 0
	v_permlane32_swap_b32_e32 v34, v36
	v_permlane32_swap_b32_e32 v35, v37
	global_store_dwordx4 v[70:71], v[38:41], off offset:160
	global_store_dwordx4 v[68:69], v[34:37], off offset:64
	global_store_dwordx4 v[70:71], v[42:45], off offset:192
	v_fmac_f32_e32 v66, v48, v48
	v_cvt_pk_bf16_f32 v34, v42, v43
	v_cvt_pk_bf16_f32 v35, v44, v45
	v_cvt_pk_bf16_f32 v36, v46, v47
	v_cvt_pk_bf16_f32 v37, v48, v49
	v_fmac_f32_e32 v66, v49, v49
	v_permlane32_swap_b32_e32 v34, v36
	v_permlane32_swap_b32_e32 v35, v37
	global_store_dwordx4 v[70:71], v[46:49], off offset:224
	global_store_dwordx4 v[68:69], v[34:37], off offset:96
	s_nop 1
	v_mov_b32_e32 v34, v66
	s_nop 1
	v_permlane32_swap_b32_e32 v66, v34
	s_and_saveexec_b64 s[82:83], vcc
	s_cbranch_execz .LBB0_302
	v_lshlrev_b64 v[36:37], 7, v[164:165]
	v_lshl_add_u64 v[36:37], s[28:29], 0, v[36:37]
	v_lshl_add_u64 v[36:37], s[0:1], 2, v[36:37]
	v_mov_b32_e32 v99, v1
	v_lshl_add_u64 v[36:37], v[36:37], 0, v[98:99]
	v_add_f32_e32 v34, v66, v34
	global_store_dword v[36:37], v34, off
; DI void out_tile(const Params& p, int l, int mi, int ni, char* lds) {
;     ...
;         const f32x4 v = *(const f32x4*)(xr + nt * 32 + 8 * g);
;         acc[mt][nt][4 * g] = v[0]; acc[mt][nt][4 * g + 1] = v[1]; acc[mt][nt][4 * g + 2] = v[2]; acc[mt][nt][4 * g + 3] = v[3];
;       }
;   }
;   gemm_main<true, false, false>(p.MIX + (size_t)m0 * 2048, 2048, p.WoutT + ((size_t)l * 2048 + n0) * 2048, 2048, 2048, lds, acc, nullptr);
; #pragma unroll
;   for (int mt = 0; mt < 4; ++mt) {
;     const size_t rowoff = (size_t)(m0 + wm * 128 + mt * 32 + r) * DM + n0 + wn * 64 + 4 * hf;
;     const size_t rowoffb = (size_t)(m0 + wm * 128 + mt * 32 + r) * DM + n0 + wn * 64 + 8 * hf;
;     float pss = 0.f;
; #pragma unroll
;     for (int nt = 0; nt < 2; ++nt)
; #pragma unroll
;       for (int a = 0; a < 2; ++a) {
;         float xq[2][4];
; #pragma unroll
;         for (int gg = 0; gg < 2; ++gg) {
;           const int g = 2 * a + gg;
;           f32x4 xo = {acc[mt][nt][4 * g], acc[mt][nt][4 * g + 1], acc[mt][nt][4 * g + 2], acc[mt][nt][4 * g + 3]};
;           *(f32x4*)(p.X + rowoff + nt * 32 + 8 * g) = xo;
;           xq[gg][0] = xo[0]; xq[gg][1] = xo[1]; xq[gg][2] = xo[2]; xq[gg][3] = xo[3];
;           pss = fmaf(xo[0], xo[0], pss); pss = fmaf(xo[1], xo[1], pss); pss = fmaf(xo[2], xo[2], pss); pss = fmaf(xo[3], xo[3], pss);
;         }
;         st8_pair_bf16(p.XB + rowoffb + nt * 32 + 16 * a, xq[0], xq[1]);
;       }
;     pss = xhalf_sum(pss);
;     if (hf == 0) p.XSS[(size_t)(m0 + wm * 128 + mt * 32 + r) * 32 + ni * 4 + wn] = pss;
;   }
.LBB0_302:
	s_or_b64 exec, exec, s[82:83]
	s_waitcnt vmcnt(24)
	v_add_f32_e32 v18, v18, v208
	v_add_f32_e32 v19, v19, v209
	v_add_f32_e32 v20, v20, v210
	v_add_f32_e32 v21, v21, v211
	v_add_f32_e32 v22, v22, v212
	v_add_f32_e32 v23, v23, v213
	v_add_f32_e32 v24, v24, v214
	v_add_f32_e32 v25, v25, v215
	v_add_f32_e32 v26, v26, v216
	v_add_f32_e32 v27, v27, v217
	v_add_f32_e32 v28, v28, v218
	v_add_f32_e32 v29, v29, v219
	v_add_f32_e32 v30, v30, v140
	v_add_f32_e32 v31, v31, v141
	v_add_f32_e32 v32, v32, v142
	v_add_f32_e32 v33, v33, v143
	v_add_f32_e32 v2, v2, v144
	v_add_f32_e32 v3, v3, v145
	v_add_f32_e32 v4, v4, v146
	v_add_f32_e32 v5, v5, v147
	v_add_f32_e32 v6, v6, v148
	v_add_f32_e32 v7, v7, v149
	v_add_f32_e32 v8, v8, v150
	v_add_f32_e32 v9, v9, v151
	v_add_f32_e32 v10, v10, v152
	v_add_f32_e32 v11, v11, v153
	v_add_f32_e32 v12, v12, v154
	v_add_f32_e32 v13, v13, v155
	v_add_f32_e32 v14, v14, v156
	v_add_f32_e32 v15, v15, v157
	v_add_f32_e32 v16, v16, v158
	v_add_f32_e32 v17, v17, v159
	v_lshlrev_b64 v[34:35], 11, v[162:163]
	v_lshl_add_u64 v[36:37], v[34:35], 0, v[130:131]
	v_lshl_add_u64 v[34:35], v[36:37], 2, s[38:39]
	v_lshl_add_u64 v[38:39], v[34:35], 0, v[132:133]
	v_fma_f32 v34, v18, v18, 0
	v_fmac_f32_e32 v34, v19, v19
	v_fmac_f32_e32 v34, v20, v20
	v_fmac_f32_e32 v34, v21, v21
	v_fmac_f32_e32 v34, v22, v22
	v_fmac_f32_e32 v34, v23, v23
	v_fmac_f32_e32 v34, v24, v24
	v_fmac_f32_e32 v34, v25, v25
	v_fmac_f32_e32 v34, v26, v26
	v_fmac_f32_e32 v34, v27, v27
	v_fmac_f32_e32 v34, v28, v28
	v_fmac_f32_e32 v34, v29, v29
	v_fmac_f32_e32 v34, v30, v30
	v_fmac_f32_e32 v34, v31, v31
	v_fmac_f32_e32 v34, v32, v32
	v_fmac_f32_e32 v34, v33, v33
	v_fmac_f32_e32 v34, v2, v2
	v_fmac_f32_e32 v34, v3, v3
	v_fmac_f32_e32 v34, v4, v4
	v_fmac_f32_e32 v34, v5, v5
	v_fmac_f32_e32 v34, v6, v6
	v_fmac_f32_e32 v34, v7, v7
	v_fmac_f32_e32 v34, v8, v8
	v_fmac_f32_e32 v34, v9, v9
	v_fmac_f32_e32 v34, v10, v10
	v_fmac_f32_e32 v34, v11, v11
	global_store_dwordx4 v[38:39], v[18:21], off
	v_lshl_add_u64 v[36:37], v[36:37], 1, s[40:41]
	v_fmac_f32_e32 v34, v12, v12
	v_cvt_pk_bf16_f32 v18, v18, v19
	v_cvt_pk_bf16_f32 v19, v20, v21
	v_cvt_pk_bf16_f32 v20, v22, v23
	v_cvt_pk_bf16_f32 v21, v24, v25
	v_lshl_add_u64 v[36:37], v[36:37], 0, v[0:1]
	v_permlane32_swap_b32_e32 v18, v20
	v_permlane32_swap_b32_e32 v19, v21
	v_fmac_f32_e32 v34, v13, v13
	global_store_dwordx4 v[38:39], v[22:25], off offset:32
	global_store_dwordx4 v[36:37], v[18:21], off
	global_store_dwordx4 v[38:39], v[26:29], off offset:64
	v_fmac_f32_e32 v34, v14, v14
	v_cvt_pk_bf16_f32 v18, v26, v27
	v_cvt_pk_bf16_f32 v19, v28, v29
	v_cvt_pk_bf16_f32 v20, v30, v31
	v_cvt_pk_bf16_f32 v21, v32, v33
	s_nop 0
	v_permlane32_swap_b32_e32 v18, v20
	v_permlane32_swap_b32_e32 v19, v21
	v_fmac_f32_e32 v34, v15, v15
	global_store_dwordx4 v[38:39], v[30:33], off offset:96
	global_store_dwordx4 v[36:37], v[18:21], off offset:32
	global_store_dwordx4 v[38:39], v[2:5], off offset:128
	v_fmac_f32_e32 v34, v16, v16
	v_fmac_f32_e32 v34, v17, v17
	v_cvt_pk_bf16_f32 v2, v2, v3
	v_cvt_pk_bf16_f32 v3, v4, v5
	v_cvt_pk_bf16_f32 v4, v6, v7
	v_cvt_pk_bf16_f32 v5, v8, v9
	s_nop 0
	v_permlane32_swap_b32_e32 v2, v4
	v_permlane32_swap_b32_e32 v3, v5
	global_store_dwordx4 v[38:39], v[6:9], off offset:160
	global_store_dwordx4 v[36:37], v[2:5], off offset:64
	global_store_dwordx4 v[38:39], v[10:13], off offset:192
	v_mov_b32_e32 v0, v34
	v_cvt_pk_bf16_f32 v2, v10, v11
	v_cvt_pk_bf16_f32 v3, v12, v13
	v_cvt_pk_bf16_f32 v4, v14, v15
	v_cvt_pk_bf16_f32 v5, v16, v17
	s_nop 0
	v_permlane32_swap_b32_e32 v2, v4
	v_permlane32_swap_b32_e32 v3, v5
	v_permlane32_swap_b32_e32 v34, v0
	global_store_dwordx4 v[38:39], v[14:17], off offset:224
	global_store_dwordx4 v[36:37], v[2:5], off offset:96
	s_and_saveexec_b64 s[82:83], vcc
	s_cbranch_execz .LBB0_289
	v_lshlrev_b64 v[2:3], 7, v[162:163]
	v_lshl_add_u64 v[2:3], s[28:29], 0, v[2:3]
	v_lshl_add_u64 v[2:3], s[0:1], 2, v[2:3]
	v_mov_b32_e32 v99, v1
	v_lshl_add_u64 v[2:3], v[2:3], 0, v[98:99]
	v_add_f32_e32 v0, v34, v0
	global_store_dword v[2:3], v0, off
	s_branch .LBB0_289
